# finalize and kv-prep loops: all loads of an iteration issued together, norm weights hoisted out of the kv-prep loop
# speedup vs baseline: 1.4349x; 1.0148x over previous
; DI int otid() { int t = threadIdx.x; asm volatile("" : "+v"(t)); return t; }
; DI float silu(float g) { return g * frcp(1.f + fexp(-g)); }
; DI uint4 pack8(const float* f) { uint4 v; v.x = pack2(f[0], f[1]); v.y = pack2(f[2], f[3]); v.z = pack2(f[4], f[5]); v.w = pack2(f[6], f[7]); return v; }
; DI void phase_finalize(const Params& p, int L, int c, bool dry) {
;     ...
;   for (int idx = blockIdx.x * 256 + otid(); idx < TC * 192; idx += G * 256) {
;     const int lr = idx / 192, c8 = idx - lr * 192, ch0 = c8 * 8, head = ch0 >> 6;
;     const float4 st = *(const float4*)(ST + (size_t)(lr * 24 + head) * 4);
;     const float mean = (st.x + st.z) * (1.f / 64.f);
;     const float var = (st.y + st.w) * (1.f / 64.f) - mean * mean;
;     const float rstd = rsqrtf(fmaxf(var, 0.f) + 64e-5f);
;     float y[8], bv[8], g[8], o[8];
;     unpack8(*(const uint4*)(YR + (size_t)lr * 1536 + ch0), y);
;     unpack8(*(const uint4*)(BV + (size_t)lr * 1536 + ch0), bv);
;     u16* gp = U + (size_t)lr * LDU_R + R_GATE + ch0;
;     unpack8(*(const uint4*)gp, g);
;     const float* gw = p.gn_w + j * 1536 + ch0; const float* gb = p.gn_b + j * 1536 + ch0;
; #pragma unroll
;     for (int e = 0; e < 8; ++e) o[e] = ((y[e] - mean) * rstd * gw[e] + gb[e] + bv[e]) * silu(g[e]);
;     if (!dry) *(uint4*)gp = pack8(o);
;   }
.LBB0_100:
	v_readlane_b32 s8, v255, 20
	v_readlane_b32 s9, v255, 21
	s_andn2_b64 vcc, exec, s[8:9]
	s_cbranch_vccnz .LBB0_99
	s_mov_b32 s8, 0x2aaaaaab
	v_mul_hi_i32 v0, v20, s8
	v_lshrrev_b32_e32 v1, 31, v0
	v_ashrrev_i32_e32 v0, 5, v0
	v_add_u32_e32 v16, v0, v1
	v_mov_b64_e32 v[0:1], s[2:3]
	v_mad_i64_i32 v[0:1], s[8:9], v16, s66, v[0:1]
	s_movk_i32 s8, 0xff40
	s_nop 0
	v_mad_u64_u32 v[4:5], s[8:9], v16, s8, v[20:21]
	s_movk_i32 s8, 0xfa00
	s_nop 0
	v_mad_u64_u32 v[8:9], s[8:9], v16, s8, v[22:23]
	v_ashrrev_i32_e32 v9, 31, v8
	v_lshlrev_b64 v[10:11], 1, v[8:9]
	v_lshl_add_u64 v[0:1], v[0:1], 0, v[10:11]
	s_movk_i32 s8, 0x2000
	v_ashrrev_i32_e32 v4, 3, v4
	v_add_co_u32_e32 v24, vcc, s8, v0
	v_mad_u64_u32 v[4:5], s[8:9], v16, 24, v[4:5]
	v_readlane_b32 s8, v252, 56
	v_ashrrev_i32_e32 v5, 31, v4
	v_readlane_b32 s9, v252, 57
	v_addc_co_u32_e32 v25, vcc, 0, v1, vcc
	s_nop 0
	v_lshl_add_u64 v[4:5], v[4:5], 4, s[8:9]
	global_load_dwordx4 v[4:7], v[4:5], off
	global_load_dwordx4 v[0:3], v[24:25], off offset:2304
	s_movk_i32 s10, 0xc00
	v_lshlrev_b64 v[44:45], 2, v[8:9]
	v_mov_b64_e32 v[46:47], s[42:43]
	v_mov_b64_e32 v[52:53], s[38:39]
	v_readlane_b32 s8, v254, 41
	v_readlane_b32 s9, v254, 42
	v_mad_i64_i32 v[46:47], vcc, v16, s10, v[46:47]
	v_mad_i64_i32 v[52:53], vcc, v16, s10, v[52:53]
	v_lshl_add_u64 v[48:49], s[8:9], 0, v[44:45]
	v_readlane_b32 s8, v254, 43
	v_readlane_b32 s9, v254, 44
	v_lshl_add_u64 v[46:47], v[46:47], 0, v[10:11]
	v_lshl_add_u64 v[52:53], v[52:53], 0, v[10:11]
	global_load_dwordx4 v[12:15], v[46:47], off
	global_load_dwordx4 v[16:19], v[52:53], off
	v_lshl_add_u64 v[50:51], s[8:9], 0, v[44:45]
	global_load_dwordx4 v[56:59], v[48:49], off offset:16
	global_load_dwordx4 v[60:63], v[48:49], off
	global_load_dwordx4 v[64:67], v[50:51], off offset:16
	global_load_dwordx4 v[68:71], v[50:51], off
	s_mov_b32 s8, 0x3c800000
	s_waitcnt vmcnt(7)
	v_pk_add_f32 v[4:5], v[4:5], v[6:7]
	s_nop 0
	v_pk_mul_f32 v[26:27], v[4:5], s[8:9] op_sel_hi:[1,0]
	s_mov_b32 s8, 0x800000
	v_fma_f32 v4, -v26, v26, v27
	v_max_f32_e32 v4, 0, v4
	v_add_f32_e32 v4, 0x3a27c5ac, v4
	v_cmp_gt_f32_e32 vcc, s8, v4
	v_mul_f32_e32 v5, 0x4b800000, v4
	s_waitcnt vmcnt(6) lgkmcnt(0)
	v_lshlrev_b32_e32 v30, 16, v0
	v_cndmask_b32_e32 v4, v4, v5, vcc
	v_rsq_f32_e32 v4, v4
	v_and_b32_e32 v31, 0xffff0000, v0
	v_mul_f32_e32 v0, 0xbfb8aa3b, v30
	v_mul_f32_e32 v5, 0x45800000, v4
	v_cndmask_b32_e32 v28, v4, v5, vcc
	v_exp_f32_e32 v0, v0
	s_waitcnt vmcnt(5)
	v_lshlrev_b32_e32 v4, 16, v12
	v_add_f32_e32 v0, 1.0, v0
	v_and_b32_e32 v5, 0xffff0000, v12
	v_rcp_f32_e32 v6, v0
	v_mul_f32_e32 v0, 0xbfb8aa3b, v31
	v_exp_f32_e32 v0, v0
	v_pk_add_f32 v[4:5], v[4:5], v[26:27] op_sel_hi:[1,0] neg_lo:[0,1] neg_hi:[0,1]
	v_lshlrev_b32_e32 v12, 16, v13
	v_pk_mul_f32 v[42:43], v[4:5], v[28:29] op_sel_hi:[1,0]
	v_add_f32_e32 v0, 1.0, v0
	v_rcp_f32_e32 v7, v0
	v_lshlrev_b32_e32 v0, 16, v1
	v_mul_f32_e32 v21, 0xbfb8aa3b, v0
	v_exp_f32_e32 v21, v21
	v_pk_mul_f32 v[40:41], v[6:7], v[30:31]
	v_and_b32_e32 v1, 0xffff0000, v1
	v_add_f32_e32 v21, 1.0, v21
	v_and_b32_e32 v13, 0xffff0000, v13
	v_pk_add_f32 v[12:13], v[12:13], v[26:27] op_sel_hi:[1,0] neg_lo:[0,1] neg_hi:[0,1]
	s_waitcnt vmcnt(4)
	v_lshlrev_b32_e32 v38, 16, v16
	v_pk_mul_f32 v[12:13], v[28:29], v[12:13] op_sel_hi:[0,1]
	v_and_b32_e32 v39, 0xffff0000, v16
	v_lshlrev_b32_e32 v16, 16, v17
	v_and_b32_e32 v17, 0xffff0000, v17
	s_waitcnt vmcnt(0)
	v_pk_fma_f32 v[30:31], v[60:61], v[42:43], v[68:69]
	v_rcp_f32_e32 v34, v21
	v_mul_f32_e32 v21, 0xbfb8aa3b, v1
	v_exp_f32_e32 v21, v21
	v_pk_fma_f32 v[12:13], v[62:63], v[12:13], v[70:71]
	v_lshlrev_b32_e32 v32, 16, v18
	v_pk_add_f32 v[12:13], v[12:13], v[16:17]
	v_add_f32_e32 v21, 1.0, v21
	v_rcp_f32_e32 v35, v21
	v_lshlrev_b32_e32 v16, 16, v14
	v_and_b32_e32 v17, 0xffff0000, v14
	v_pk_add_f32 v[16:17], v[16:17], v[26:27] op_sel_hi:[1,0] neg_lo:[0,1] neg_hi:[0,1]
	v_pk_mul_f32 v[0:1], v[34:35], v[0:1]
	v_pk_mul_f32 v[16:17], v[28:29], v[16:17] op_sel_hi:[0,1]
	v_pk_mul_f32 v[0:1], v[0:1], v[12:13]
	v_lshlrev_b32_e32 v12, 16, v2
	v_and_b32_e32 v13, 0xffff0000, v2
	v_mul_f32_e32 v2, 0xbfb8aa3b, v12
	v_exp_f32_e32 v2, v2
	v_pk_fma_f32 v[4:5], v[56:57], v[16:17], v[64:65]
	v_lshlrev_b32_e32 v8, 16, v15
	v_and_b32_e32 v9, 0xffff0000, v15
	v_add_f32_e32 v2, 1.0, v2
	v_rcp_f32_e32 v34, v2
	v_mul_f32_e32 v2, 0xbfb8aa3b, v13
	v_exp_f32_e32 v2, v2
	v_and_b32_e32 v33, 0xffff0000, v18
	v_pk_add_f32 v[8:9], v[8:9], v[26:27] op_sel_hi:[1,0] neg_lo:[0,1] neg_hi:[0,1]
	v_pk_add_f32 v[4:5], v[4:5], v[32:33]
	v_add_f32_e32 v2, 1.0, v2
	v_rcp_f32_e32 v35, v2
	v_lshlrev_b32_e32 v2, 16, v3
	v_and_b32_e32 v3, 0xffff0000, v3
	v_mul_f32_e32 v14, 0xbfb8aa3b, v2
	v_mul_f32_e32 v15, 0xbfb8aa3b, v3
	v_exp_f32_e32 v14, v14
	v_exp_f32_e32 v15, v15
	v_pk_mul_f32 v[12:13], v[34:35], v[12:13]
	v_pk_mul_f32 v[8:9], v[28:29], v[8:9] op_sel_hi:[0,1]
	v_add_f32_e32 v14, 1.0, v14
	v_add_f32_e32 v15, 1.0, v15
	v_rcp_f32_e32 v14, v14
	v_rcp_f32_e32 v15, v15
	v_pk_mul_f32 v[4:5], v[12:13], v[4:5]
	v_lshlrev_b32_e32 v12, 16, v19
	v_and_b32_e32 v13, 0xffff0000, v19
	v_pk_fma_f32 v[6:7], v[58:59], v[8:9], v[66:67]
	v_pk_add_f32 v[30:31], v[30:31], v[38:39]
	v_pk_mul_f32 v[2:3], v[14:15], v[2:3]
	v_pk_add_f32 v[6:7], v[6:7], v[12:13]
	v_pk_mul_f32 v[30:31], v[40:41], v[30:31]
	v_pk_mul_f32 v[6:7], v[2:3], v[6:7]
	v_cvt_pk_bf16_f32 v2, v30, v31
	v_cvt_pk_bf16_f32 v3, v0, v1
	v_cvt_pk_bf16_f32 v4, v4, v5
	v_cvt_pk_bf16_f32 v5, v6, v7
	global_store_dwordx4 v[24:25], v[2:5], off offset:2304
	s_branch .LBB0_99

; DI int otid() { int t = threadIdx.x; asm volatile("" : "+v"(t)); return t; }
; DI float wave_sum(float v) { for (int o = 32; o > 0; o >>= 1) v += __shfl_xor(v, o); return v; }
; DI uint4 pack8(const float* f) { uint4 v; v.x = pack2(f[0], f[1]); v.y = pack2(f[2], f[3]); v.z = pack2(f[4], f[5]); v.w = pack2(f[6], f[7]); return v; }
; DI void phase_kvprep(const Params& p, int L, int c, bool dry) {
;   const int tid = otid(), w = tid >> 6, lane = tid & 63;
;   const int j = L >> 1;
;   u16* U = (u16*)(p.ws + OFF_U); u16* Kb = (u16*)(p.ws + OFF_K);
;   const float* cs = (const float*)(p.ws + OFF_COS); const float* sn = (const float*)(p.ws + OFF_SIN);
;   for (int lr = blockIdx.x * 4 + w; lr < TC; lr += gridDim.x * 4) {
;     u16* row = U + (size_t)lr * LDU_M;
;     float fq[8], fk[8]; float sq = 0.f, sk = 0.f;
;     if (lane < 48) { uint4 v = *(const uint4*)(row + M_CQ + lane * 8); unpack8(v, fq);
; #pragma unroll
;       for (int e = 0; e < 8; ++e) sq += fq[e] * fq[e]; }
;     if (lane < 32) { uint4 v = *(const uint4*)(row + M_CKV + lane * 8); unpack8(v, fk);
; #pragma unroll
;       for (int e = 0; e < 8; ++e) sk += fk[e] * fk[e]; }
;     sq = wave_sum(sq); sk = wave_sum(sk);
;     float rq = rsqrtf(sq * (1.f / 384.f) + 1e-6f), rk = rsqrtf(sk * (1.f / 256.f) + 1e-6f);
;     if (dry) continue;
;     if (lane < 48) {
;       const float* g = p.q_norm_g + j * 384 + lane * 8;
; #pragma unroll
;       for (int e = 0; e < 8; ++e) fq[e] = fq[e] * rq * g[e];
;       *(uint4*)(row + M_CQ + lane * 8) = pack8(fq);
;     }
;     if (lane < 32) {
;       const float* g = p.kv_norm_g + j * 256 + lane * 8;
; #pragma unroll
;       for (int e = 0; e < 8; ++e) fk[e] = fk[e] * rk * g[e];
;       *(uint4*)(row + M_CKV + lane * 8) = pack8(fk);
;     }
;     if (lane < 8) {
.LBB0_404:
	s_and_b64 vcc, exec, s[0:1]
	s_cbranch_vccz .LBB0_421
	v_mov_b32_e32 v1, v197
	v_readlane_b32 s0, v254, 1
	v_ashrrev_i32_e32 v0, 6, v1
	v_readlane_b32 s1, v254, 2
	s_waitcnt vmcnt(0)
	v_add_u32_e32 v21, s0, v0
	s_movk_i32 s0, 0x4000
	v_cmp_gt_i32_e32 vcc, s0, v21
	s_and_saveexec_b64 s[12:13], vcc
	s_cbranch_execz .LBB0_420
	v_cmp_lt_i32_e32 vcc, v213, v211
	v_and_b32_e32 v1, 63, v1
	v_readlane_b32 s0, v254, 60
	v_cndmask_b32_e32 v2, v210, v213, vcc
	v_lshlrev_b32_e32 v32, 2, v2
	v_accvgpr_read_b32 v2, a203
	v_cmp_lt_i32_e32 vcc, v2, v211
	v_lshlrev_b32_e32 v198, 5, v1
	v_readlane_b32 s1, v254, 61
	v_cndmask_b32_e32 v2, v210, v2, vcc
	v_lshlrev_b32_e32 v33, 2, v2
	v_accvgpr_read_b32 v2, a204
	v_cmp_lt_i32_e32 vcc, v2, v211
	v_lshl_add_u64 v[22:23], s[0:1], 0, v[198:199]
	v_readlane_b32 s0, v254, 62
	v_cndmask_b32_e32 v2, v210, v2, vcc
	v_lshlrev_b32_e32 v34, 2, v2
	v_accvgpr_read_b32 v2, a205
	v_cmp_lt_i32_e32 vcc, v2, v211
	v_readlane_b32 s1, v254, 63
	v_lshlrev_b32_e32 v0, 5, v0
	v_cndmask_b32_e32 v2, v210, v2, vcc
	v_lshlrev_b32_e32 v35, 2, v2
	v_accvgpr_read_b32 v2, a206
	v_cmp_lt_i32_e32 vcc, v2, v211
	v_lshl_add_u64 v[24:25], s[0:1], 0, v[198:199]
	v_readlane_b32 s0, v255, 10
	v_cndmask_b32_e32 v2, v210, v2, vcc
	v_lshlrev_b32_e32 v36, 2, v2
	v_accvgpr_read_b32 v2, a207
	v_cmp_lt_i32_e32 vcc, v2, v211
	v_mov_b32_e32 v198, v199
	v_cmp_gt_u32_e64 s[6:7], 48, v1
	v_cndmask_b32_e32 v2, v210, v2, vcc
	v_lshlrev_b32_e32 v37, 2, v2
	v_lshlrev_b32_e32 v2, 2, v1
	v_lshlrev_b32_e32 v20, 3, v1
	v_cmp_gt_u32_e64 s[8:9], 32, v1
	v_cmp_gt_u32_e64 s[10:11], 8, v1
	v_add3_u32 v26, s0, v0, v2
	v_mov_b32_e32 v200, v199
	v_mov_b32_e32 v201, v199
	v_mov_b32_e32 v202, v199
	v_mov_b32_e32 v203, v199
	v_mov_b32_e32 v204, v199
	v_mov_b32_e32 v205, v199
	v_mov_b64_e32 v[0:1], v[198:199]
	v_mov_b64_e32 v[8:9], v[198:199]
	s_mov_b64 s[14:15], 0
	v_mov_b64_e32 v[2:3], v[200:201]
	v_mov_b64_e32 v[4:5], v[202:203]
	v_mov_b64_e32 v[6:7], v[204:205]
	v_mov_b64_e32 v[10:11], v[200:201]
	v_mov_b64_e32 v[12:13], v[202:203]
	v_mov_b64_e32 v[14:15], v[204:205]
	s_and_saveexec_b64 s[0:1], s[6:7]
	global_load_dwordx4 v[72:75], v[22:23], off offset:16
	global_load_dwordx4 v[76:79], v[22:23], off
	s_or_b64 exec, exec, s[0:1]
	s_and_saveexec_b64 s[0:1], s[8:9]
	global_load_dwordx4 v[80:83], v[24:25], off offset:16
	global_load_dwordx4 v[84:87], v[24:25], off
	s_or_b64 exec, exec, s[0:1]
	s_branch .LBB0_409

; DI float wave_sum(float v) { for (int o = 32; o > 0; o >>= 1) v += __shfl_xor(v, o); return v; }
; DI uint4 pack8(const float* f) { uint4 v; v.x = pack2(f[0], f[1]); v.y = pack2(f[2], f[3]); v.z = pack2(f[4], f[5]); v.w = pack2(f[6], f[7]); return v; }
; DI void phase_kvprep(const Params& p, int L, int c, bool dry) {
;     ...
;   for (int lr = blockIdx.x * 4 + w; lr < TC; lr += gridDim.x * 4) {
;     u16* row = U + (size_t)lr * LDU_M;
;     float fq[8], fk[8]; float sq = 0.f, sk = 0.f;
;     if (lane < 48) { uint4 v = *(const uint4*)(row + M_CQ + lane * 8); unpack8(v, fq);
; #pragma unroll
;       for (int e = 0; e < 8; ++e) sq += fq[e] * fq[e]; }
;     if (lane < 32) { uint4 v = *(const uint4*)(row + M_CKV + lane * 8); unpack8(v, fk);
; #pragma unroll
;       for (int e = 0; e < 8; ++e) sk += fk[e] * fk[e]; }
;     sq = wave_sum(sq); sk = wave_sum(sk);
;     float rq = rsqrtf(sq * (1.f / 384.f) + 1e-6f), rk = rsqrtf(sk * (1.f / 256.f) + 1e-6f);
;     if (dry) continue;
;     if (lane < 48) {
;       const float* g = p.q_norm_g + j * 384 + lane * 8;
; #pragma unroll
;       for (int e = 0; e < 8; ++e) fq[e] = fq[e] * rq * g[e];
;       *(uint4*)(row + M_CQ + lane * 8) = pack8(fq);
;     }
;     if (lane < 32) {
;       const float* g = p.kv_norm_g + j * 256 + lane * 8;
; #pragma unroll
;       for (int e = 0; e < 8; ++e) fk[e] = fk[e] * rk * g[e];
;       *(uint4*)(row + M_CKV + lane * 8) = pack8(fk);
;     }
;     ...
;       float f[8], o[8]; uint4 v = *(const uint4*)(row + M_KR + lane * 8); unpack8(v, f);
;       int gt = c * 16384 + lr;
; #pragma unroll
;       for (int i = 0; i < 4; ++i) {
;         float cc = cs[gt * 32 + lane * 4 + i], ss = sn[gt * 32 + lane * 4 + i];
.LBB0_409:
	v_mov_b64_e32 v[16:17], s[2:3]
	s_movk_i32 s0, 0x1980
	v_mad_i64_i32 v[16:17], s[0:1], v21, s0, v[16:17]
	v_mov_b32_e32 v18, 0
	v_lshlrev_b32_e32 v198, 1, v20
	v_mov_b32_e32 v19, 0
	s_and_saveexec_b64 s[0:1], s[10:11]
	v_readlane_b32 s16, v253, 11
	v_readlane_b32 s17, v253, 12
	v_readlane_b32 s18, v253, 13
	v_readlane_b32 s19, v253, 14
	v_lshl_add_u64 v[68:69], v[16:17], 0, v[198:199]
	global_load_dwordx4 v[48:51], v[68:69], off offset:1280
	v_add_u32_e32 v68, -3, v26
	v_ashrrev_i32_e32 v69, 31, v68
	v_lshlrev_b64 v[68:69], 2, v[68:69]
	v_lshl_add_u64 v[70:71], s[18:19], 0, v[68:69]
	v_lshl_add_u64 v[68:69], s[16:17], 0, v[68:69]
	global_load_dword v52, v[70:71], off
	global_load_dword v54, v[68:69], off
	v_add_u32_e32 v68, -2, v26
	v_ashrrev_i32_e32 v69, 31, v68
	v_lshlrev_b64 v[68:69], 2, v[68:69]
	v_lshl_add_u64 v[70:71], s[18:19], 0, v[68:69]
	v_lshl_add_u64 v[68:69], s[16:17], 0, v[68:69]
	global_load_dword v56, v[70:71], off
	global_load_dword v58, v[68:69], off
	v_add_u32_e32 v68, -1, v26
	v_ashrrev_i32_e32 v69, 31, v68
	v_lshlrev_b64 v[68:69], 2, v[68:69]
	v_lshl_add_u64 v[70:71], s[18:19], 0, v[68:69]
	v_lshl_add_u64 v[68:69], s[16:17], 0, v[68:69]
	global_load_dword v60, v[70:71], off
	global_load_dword v62, v[68:69], off
	v_add_u32_e32 v68, 0, v26
	v_ashrrev_i32_e32 v69, 31, v68
	v_lshlrev_b64 v[68:69], 2, v[68:69]
	v_lshl_add_u64 v[70:71], s[18:19], 0, v[68:69]
	v_lshl_add_u64 v[68:69], s[16:17], 0, v[68:69]
	global_load_dword v64, v[70:71], off
	global_load_dword v66, v[68:69], off
	s_or_b64 exec, exec, s[0:1]
	s_and_saveexec_b64 s[0:1], s[8:9]
	v_lshl_add_u64 v[68:69], v[16:17], 0, v[198:199]
	global_load_dwordx4 v[12:15], v[68:69], off offset:768
	s_or_b64 exec, exec, s[0:1]
	s_and_saveexec_b64 s[0:1], s[6:7]
	s_cbranch_execz .LBB0_411
	v_lshl_add_u64 v[0:1], v[16:17], 0, v[198:199]
	global_load_dwordx4 v[4:7], v[0:1], off
	s_waitcnt vmcnt(0)
	v_lshlrev_b32_e32 v0, 16, v4
	v_and_b32_e32 v1, 0xffff0000, v4
	v_lshlrev_b32_e32 v2, 16, v5
	v_and_b32_e32 v3, 0xffff0000, v5
	s_waitcnt lgkmcnt(0)
	v_pk_mul_f32 v[28:29], v[0:1], v[0:1]
	s_waitcnt lgkmcnt(0)
	v_mov_b32_e32 v30, v3
	v_mov_b32_e32 v31, v2
	v_lshlrev_b32_e32 v4, 16, v6
	v_and_b32_e32 v5, 0xffff0000, v6
	v_pk_mul_f32 v[30:31], v[30:31], v[30:31]
	v_add_f32_e32 v19, v28, v29
	v_mov_b32_e32 v38, v5
	v_mov_b32_e32 v39, v4
	v_add_f32_e32 v19, v19, v31
	v_lshlrev_b32_e32 v6, 16, v7
	v_and_b32_e32 v7, 0xffff0000, v7
	v_pk_mul_f32 v[38:39], v[38:39], v[38:39]
	v_add_f32_e32 v19, v30, v19
	v_mov_b32_e32 v40, v7
	v_mov_b32_e32 v41, v6
	v_add_f32_e32 v19, v39, v19
	v_pk_mul_f32 v[40:41], v[40:41], v[40:41]
	v_add_f32_e32 v19, v38, v19
	v_add_f32_e32 v19, v41, v19
	v_add_f32_e32 v19, v40, v19
.LBB0_411:
	s_or_b64 exec, exec, s[0:1]
	s_and_saveexec_b64 s[0:1], s[8:9]
	s_cbranch_execz .LBB0_413
	v_lshlrev_b32_e32 v8, 16, v12
	v_and_b32_e32 v9, 0xffff0000, v12
	v_lshlrev_b32_e32 v10, 16, v13
	v_and_b32_e32 v11, 0xffff0000, v13
	s_waitcnt lgkmcnt(0)
	v_pk_mul_f32 v[28:29], v[8:9], v[8:9]
	s_waitcnt lgkmcnt(0)
	v_mov_b32_e32 v30, v11
	v_mov_b32_e32 v31, v10
	v_lshlrev_b32_e32 v12, 16, v14
	v_and_b32_e32 v13, 0xffff0000, v14
	v_pk_mul_f32 v[30:31], v[30:31], v[30:31]
	v_add_f32_e32 v18, v28, v29
	v_mov_b32_e32 v38, v13
	v_mov_b32_e32 v39, v12
	v_add_f32_e32 v18, v18, v31
	v_lshlrev_b32_e32 v14, 16, v15
	v_and_b32_e32 v15, 0xffff0000, v15
	v_pk_mul_f32 v[38:39], v[38:39], v[38:39]
	v_add_f32_e32 v18, v30, v18
	v_mov_b32_e32 v40, v15
	v_mov_b32_e32 v41, v14
	v_add_f32_e32 v18, v39, v18
	v_pk_mul_f32 v[40:41], v[40:41], v[40:41]
	v_add_f32_e32 v18, v38, v18
	v_add_f32_e32 v18, v41, v18
	v_add_f32_e32 v18, v40, v18
.LBB0_413:
	s_or_b64 exec, exec, s[0:1]
	s_waitcnt vmcnt(0)
	s_waitcnt lgkmcnt(1)
	ds_bpermute_b32 v29, v32, v19
	s_waitcnt lgkmcnt(1)
	ds_bpermute_b32 v28, v32, v18
	v_readlane_b32 s0, v255, 20
	v_readlane_b32 s1, v255, 21
	s_andn2_b64 vcc, exec, s[0:1]
	s_waitcnt lgkmcnt(0)
	v_pk_add_f32 v[18:19], v[18:19], v[28:29]
	ds_bpermute_b32 v29, v33, v19
	ds_bpermute_b32 v28, v33, v18
	s_waitcnt lgkmcnt(0)
	v_pk_add_f32 v[18:19], v[18:19], v[28:29]
	ds_bpermute_b32 v29, v34, v19
	ds_bpermute_b32 v28, v34, v18
	s_waitcnt lgkmcnt(0)
	v_pk_add_f32 v[18:19], v[18:19], v[28:29]
	ds_bpermute_b32 v29, v35, v19
	ds_bpermute_b32 v28, v35, v18
	s_waitcnt lgkmcnt(0)
	v_pk_add_f32 v[18:19], v[18:19], v[28:29]
	ds_bpermute_b32 v29, v36, v19
	ds_bpermute_b32 v28, v36, v18
	s_waitcnt lgkmcnt(0)
	v_pk_add_f32 v[18:19], v[18:19], v[28:29]
	ds_bpermute_b32 v29, v37, v19
	ds_bpermute_b32 v28, v37, v18
	s_cbranch_vccnz .LBB0_408
	s_mov_b32 s0, 0x3b800000
	s_waitcnt lgkmcnt(0)
	v_pk_add_f32 v[18:19], v[18:19], v[28:29]
	s_mov_b32 s1, 0x3b2aaaab
	v_pk_fma_f32 v[18:19], v[18:19], s[0:1], v[206:207] op_sel_hi:[1,1,0]
	s_mov_b32 s16, 0x800000
	v_cmp_gt_f32_e64 s[0:1], s16, v19
	v_cmp_gt_f32_e32 vcc, s16, v18
	s_and_saveexec_b64 s[16:17], s[6:7]
	s_cbranch_execz .LBB0_417
	v_mul_f32_e32 v27, 0x4b800000, v19
	v_cndmask_b32_e64 v19, v19, v27, s[0:1]
	v_rsq_f32_e32 v19, v19
	s_nop 0
	v_mul_f32_e32 v27, 0x45800000, v19
	v_cndmask_b32_e64 v42, v19, v27, s[0:1]
	v_pk_mul_f32 v[0:1], v[0:1], v[42:43] op_sel_hi:[1,0]
	v_pk_mul_f32 v[2:3], v[2:3], v[42:43] op_sel_hi:[1,0]
	v_pk_mul_f32 v[4:5], v[4:5], v[42:43] op_sel_hi:[1,0]
	v_pk_mul_f32 v[6:7], v[6:7], v[42:43] op_sel_hi:[1,0]
	v_pk_mul_f32 v[4:5], v[4:5], v[72:73]
	v_pk_mul_f32 v[0:1], v[0:1], v[76:77]
	v_pk_mul_f32 v[2:3], v[2:3], v[78:79]
	v_pk_mul_f32 v[6:7], v[6:7], v[74:75]
	v_cvt_pk_bf16_f32 v28, v0, v1
	v_cvt_pk_bf16_f32 v29, v2, v3
	v_cvt_pk_bf16_f32 v30, v4, v5
	v_cvt_pk_bf16_f32 v31, v6, v7
	v_lshl_add_u64 v[38:39], v[16:17], 0, v[198:199]
	global_store_dwordx4 v[38:39], v[28:31], off
	s_or_b64 exec, exec, s[16:17]
	s_and_saveexec_b64 s[0:1], s[8:9]
	s_cbranch_execnz .LBB0_418

; DI uint4 pack8(const float* f) { uint4 v; v.x = pack2(f[0], f[1]); v.y = pack2(f[2], f[3]); v.z = pack2(f[4], f[5]); v.w = pack2(f[6], f[7]); return v; }
; DI void phase_kvprep(const Params& p, int L, int c, bool dry) {
;     ...
;     if (lane < 32) {
;       const float* g = p.kv_norm_g + j * 256 + lane * 8;
; #pragma unroll
;       for (int e = 0; e < 8; ++e) fk[e] = fk[e] * rk * g[e];
;       *(uint4*)(row + M_CKV + lane * 8) = pack8(fk);
;     }
.LBB0_418:
	v_mul_f32_e32 v19, 0x4b800000, v18
	v_cndmask_b32_e32 v18, v18, v19, vcc
	v_rsq_f32_e32 v18, v18
	s_nop 0
	v_mul_f32_e32 v19, 0x45800000, v18
	v_cndmask_b32_e32 v18, v18, v19, vcc
	v_pk_mul_f32 v[8:9], v[8:9], v[18:19] op_sel_hi:[1,0]
	v_pk_mul_f32 v[10:11], v[10:11], v[18:19] op_sel_hi:[1,0]
	v_pk_mul_f32 v[12:13], v[12:13], v[18:19] op_sel_hi:[1,0]
	v_pk_mul_f32 v[14:15], v[14:15], v[18:19] op_sel_hi:[1,0]
	v_lshl_add_u64 v[18:19], v[16:17], 0, v[198:199]
	v_pk_mul_f32 v[12:13], v[12:13], v[80:81]
	v_pk_mul_f32 v[8:9], v[8:9], v[84:85]
	v_pk_mul_f32 v[10:11], v[10:11], v[86:87]
	v_pk_mul_f32 v[14:15], v[14:15], v[82:83]
	v_cvt_pk_bf16_f32 v28, v8, v9
	v_cvt_pk_bf16_f32 v29, v10, v11
	v_cvt_pk_bf16_f32 v30, v12, v13
	v_cvt_pk_bf16_f32 v31, v14, v15
	global_store_dwordx4 v[18:19], v[28:31], off offset:768
	s_or_b64 exec, exec, s[0:1]
	s_and_saveexec_b64 s[0:1], s[10:11]
	s_cbranch_execz .LBB0_407
; DI uint4 pack8(const float* f) { uint4 v; v.x = pack2(f[0], f[1]); v.y = pack2(f[2], f[3]); v.z = pack2(f[4], f[5]); v.w = pack2(f[6], f[7]); return v; }
; DI void phase_kvprep(const Params& p, int L, int c, bool dry) {
;     ...
;     if (lane < 8) {
;       float f[8], o[8]; uint4 v = *(const uint4*)(row + M_KR + lane * 8); unpack8(v, f);
;       int gt = c * 16384 + lr;
; #pragma unroll
;       for (int i = 0; i < 4; ++i) {
;         float cc = cs[gt * 32 + lane * 4 + i], ss = sn[gt * 32 + lane * 4 + i];
;         o[2 * i] = f[2 * i] * cc - f[2 * i + 1] * ss; o[2 * i + 1] = f[2 * i] * ss + f[2 * i + 1] * cc;
;       }
;       uint4 pk = pack8(o);
;       int lb = lr >> 13, s = lr & 8191;
; #pragma unroll
;       for (int hd = 0; hd < 12; ++hd) *(uint4*)(Kb + ((size_t)(lb * 12 + hd) * 8192 + s) * 192 + 128 + lane * 8) = pk;
;     }
.LBB0_419:
	v_ashrrev_i32_e32 v27, 31, v26
	v_lshlrev_b32_e32 v28, 16, v48
	v_and_b32_e32 v29, 0xffff0000, v48
	v_lshlrev_b32_e32 v16, 16, v49
	v_pk_mul_f32 v[38:39], v[52:53], v[28:29] op_sel:[0,1] op_sel_hi:[0,0]
	v_and_b32_e32 v17, 0xffff0000, v49
	v_pk_fma_f32 v[42:43], v[54:55], v[28:29], v[38:39] neg_lo:[0,0,1] neg_hi:[0,0,1]
	v_pk_fma_f32 v[28:29], v[54:55], v[28:29], v[38:39] op_sel_hi:[0,1,1]
	v_lshlrev_b32_e32 v30, 16, v50
	v_and_b32_e32 v31, 0xffff0000, v50
	v_lshlrev_b32_e32 v18, 16, v51
	v_and_b32_e32 v19, 0xffff0000, v51
	v_pk_mul_f32 v[38:39], v[56:57], v[16:17] op_sel:[0,1] op_sel_hi:[0,0]
	s_nop 0
	v_pk_fma_f32 v[40:41], v[58:59], v[16:17], v[38:39] neg_lo:[0,0,1] neg_hi:[0,0,1]
	v_pk_fma_f32 v[16:17], v[58:59], v[16:17], v[38:39] op_sel_hi:[0,1,1]
	v_pk_mul_f32 v[38:39], v[60:61], v[30:31] op_sel:[0,1] op_sel_hi:[0,0]
	s_nop 0
	v_pk_fma_f32 v[44:45], v[62:63], v[30:31], v[38:39] neg_lo:[0,0,1] neg_hi:[0,0,1]
	v_pk_fma_f32 v[30:31], v[62:63], v[30:31], v[38:39] op_sel_hi:[0,1,1]
	v_ashrrev_i32_e32 v27, 13, v21
	v_readlane_b32 s16, v252, 21
	v_readlane_b32 s18, v252, 23
	v_readlane_b32 s19, v252, 24
	v_readlane_b32 s17, v252, 22
	v_pk_mul_f32 v[38:39], v[64:65], v[18:19] op_sel:[0,1] op_sel_hi:[0,0]
	s_nop 0
	v_pk_fma_f32 v[46:47], v[66:67], v[18:19], v[38:39] neg_lo:[0,0,1] neg_hi:[0,0,1]
	v_pk_fma_f32 v[18:19], v[66:67], v[18:19], v[38:39] op_sel_hi:[0,1,1]
	v_mul_i32_i24_e32 v38, 12, v27
	v_ashrrev_i32_e32 v39, 31, v38
	v_cvt_pk_bf16_f32 v16, v42, v29
	v_cvt_pk_bf16_f32 v18, v44, v31
	v_and_b32_e32 v44, 0x1fff, v21
	v_lshlrev_b64 v[28:29], 13, v[38:39]
	v_or_b32_e32 v28, v28, v44
	v_mov_b64_e32 v[30:31], s[18:19]
	s_movk_i32 s18, 0x180
	v_cvt_pk_bf16_f32 v17, v40, v17
	v_mad_u64_u32 v[40:41], s[16:17], v28, s18, v[30:31]
	v_mad_i32_i24 v41, v29, s18, v41
	v_lshl_add_u64 v[40:41], v[40:41], 0, v[198:199]
	s_mov_b32 s19, 0x12f6c000
	v_add_co_u32_e32 v40, vcc, s19, v40
	v_cvt_pk_bf16_f32 v19, v46, v19
	s_nop 0
	v_addc_co_u32_e32 v41, vcc, 0, v41, vcc
	global_store_dwordx4 v[40:41], v[16:19], off offset:2944
	v_or_b32_e32 v40, 1, v38
	v_ashrrev_i32_e32 v41, 31, v40
	v_lshlrev_b64 v[40:41], 13, v[40:41]
	v_or_b32_e32 v27, v40, v44
	v_mad_u64_u32 v[42:43], s[16:17], v27, s18, v[30:31]
	v_mad_i32_i24 v43, v41, s18, v43
	v_lshl_add_u64 v[40:41], v[42:43], 0, v[198:199]
	v_add_co_u32_e32 v40, vcc, s19, v40
	s_nop 1
	v_addc_co_u32_e32 v41, vcc, 0, v41, vcc
	global_store_dwordx4 v[40:41], v[16:19], off offset:2944
	v_or_b32_e32 v40, 2, v38
	v_ashrrev_i32_e32 v41, 31, v40
	v_lshlrev_b64 v[40:41], 13, v[40:41]
	v_or_b32_e32 v27, v40, v44
	v_mad_u64_u32 v[42:43], s[16:17], v27, s18, v[30:31]
	v_mad_i32_i24 v43, v41, s18, v43
	v_or_b32_e32 v38, 3, v38
	v_lshl_add_u64 v[40:41], v[42:43], 0, v[198:199]
	v_ashrrev_i32_e32 v39, 31, v38
	v_add_co_u32_e32 v40, vcc, s19, v40
	v_lshlrev_b64 v[38:39], 13, v[38:39]
	s_nop 0
	v_addc_co_u32_e32 v41, vcc, 0, v41, vcc
	v_or_b32_e32 v27, v38, v44
	global_store_dwordx4 v[40:41], v[16:19], off offset:2944
	v_mad_u64_u32 v[40:41], s[16:17], v27, s18, v[30:31]
	v_mad_i32_i24 v41, v39, s18, v41
	v_lshl_add_u64 v[38:39], v[40:41], 0, v[198:199]
	v_add_co_u32_e32 v38, vcc, s19, v38
	s_mov_b64 s[16:17], 0x8000
	s_nop 0
	v_addc_co_u32_e32 v39, vcc, 0, v39, vcc
	global_store_dwordx4 v[38:39], v[16:19], off offset:2944
	v_lshl_add_u64 v[38:39], v[28:29], 0, s[16:17]
	v_mad_u64_u32 v[40:41], s[16:17], v38, s18, v[30:31]
	v_mad_i32_i24 v41, v39, s18, v41
	v_lshl_add_u64 v[38:39], v[40:41], 0, v[198:199]
	v_add_co_u32_e32 v38, vcc, s19, v38
	s_mov_b64 s[16:17], 0xa000
	s_nop 0
	v_addc_co_u32_e32 v39, vcc, 0, v39, vcc
	global_store_dwordx4 v[38:39], v[16:19], off offset:2944
	v_lshl_add_u64 v[38:39], v[28:29], 0, s[16:17]
	v_mad_u64_u32 v[40:41], s[16:17], v38, s18, v[30:31]
	v_mad_i32_i24 v41, v39, s18, v41
	v_lshl_add_u64 v[38:39], v[40:41], 0, v[198:199]
	v_add_co_u32_e32 v38, vcc, s19, v38
	s_mov_b64 s[16:17], 0xc000
	s_nop 0
	v_addc_co_u32_e32 v39, vcc, 0, v39, vcc
	global_store_dwordx4 v[38:39], v[16:19], off offset:2944
	v_lshl_add_u64 v[38:39], v[28:29], 0, s[16:17]
	v_mad_u64_u32 v[40:41], s[16:17], v38, s18, v[30:31]
	v_mad_i32_i24 v41, v39, s18, v41
	v_lshl_add_u64 v[38:39], v[40:41], 0, v[198:199]
	v_add_co_u32_e32 v38, vcc, s19, v38
	s_mov_b64 s[16:17], 0xe000
	s_nop 0
	v_addc_co_u32_e32 v39, vcc, 0, v39, vcc
	global_store_dwordx4 v[38:39], v[16:19], off offset:2944
	v_lshl_add_u64 v[38:39], v[28:29], 0, s[16:17]
	v_mad_u64_u32 v[40:41], s[16:17], v38, s18, v[30:31]
	v_mad_i32_i24 v41, v39, s18, v41
	v_lshl_add_u64 v[38:39], v[40:41], 0, v[198:199]
	v_add_co_u32_e32 v38, vcc, s19, v38
	s_mov_b64 s[16:17], 0x10000
	s_nop 0
	v_addc_co_u32_e32 v39, vcc, 0, v39, vcc
	global_store_dwordx4 v[38:39], v[16:19], off offset:2944
	v_lshl_add_u64 v[38:39], v[28:29], 0, s[16:17]
	v_mad_u64_u32 v[40:41], s[16:17], v38, s18, v[30:31]
	v_mad_i32_i24 v41, v39, s18, v41
	v_lshl_add_u64 v[38:39], v[40:41], 0, v[198:199]
	v_add_co_u32_e32 v38, vcc, s19, v38
	s_mov_b64 s[16:17], 0x12000
	s_nop 0
	v_addc_co_u32_e32 v39, vcc, 0, v39, vcc
	global_store_dwordx4 v[38:39], v[16:19], off offset:2944
	v_lshl_add_u64 v[38:39], v[28:29], 0, s[16:17]
	v_mad_u64_u32 v[40:41], s[16:17], v38, s18, v[30:31]
	v_mad_i32_i24 v41, v39, s18, v41
	v_lshl_add_u64 v[38:39], v[40:41], 0, v[198:199]
	v_add_co_u32_e32 v38, vcc, s19, v38
	s_mov_b64 s[16:17], 0x14000
	s_nop 0
	v_addc_co_u32_e32 v39, vcc, 0, v39, vcc
	global_store_dwordx4 v[38:39], v[16:19], off offset:2944
	v_lshl_add_u64 v[38:39], v[28:29], 0, s[16:17]
	v_mad_u64_u32 v[40:41], s[16:17], v38, s18, v[30:31]
	s_mov_b64 s[16:17], 0x16000
	v_mad_i32_i24 v41, v39, s18, v41
	v_lshl_add_u64 v[28:29], v[28:29], 0, s[16:17]
	v_lshl_add_u64 v[38:39], v[40:41], 0, v[198:199]
	v_mad_u64_u32 v[30:31], s[16:17], v28, s18, v[30:31]
	v_add_co_u32_e32 v38, vcc, s19, v38
	v_mad_i32_i24 v31, v29, s18, v31
	s_nop 0
	v_addc_co_u32_e32 v39, vcc, 0, v39, vcc
	v_lshl_add_u64 v[28:29], v[30:31], 0, v[198:199]
	v_add_co_u32_e32 v28, vcc, 0x12f6c000, v28
	global_store_dwordx4 v[38:39], v[16:19], off offset:2944
	s_nop 0
	v_addc_co_u32_e32 v29, vcc, 0, v29, vcc
	global_store_dwordx4 v[28:29], v[16:19], off offset:2944
	s_branch .LBB0_407
